# attn tile loop: second DMA pieces via +0x2000 VGPR offset (no 64-bit scalar adds)
# baseline (speedup 1.0000x reference)
; #define SBAR() __builtin_amdgcn_sched_barrier(0)
; #define WAIT_BAR(N) asm volatile("s_waitcnt vmcnt(" #N ") lgkmcnt(0)\n\ts_barrier":::"memory")
;   #define KRD(kp_) do{ _Pragma("unroll") for(int d0_=0;d0_<4;++d0_){ kf[2*d0_]=LDK(kp_,d0_*2048); kf[2*d0_+1]=LDK(kp_,d0_*2048+512); } }while(0)
; template<int THRL> __device__ __forceinline__ void attn_unit(int b,int h,int qb,const AttnArgs&A,char*shm,bool setup){
;     ...
;   DMA_V(1,SLOT16); { const unsigned char*g_=imgS+((size_t)(NT>2?2:NT-1)<<15); const unsigned d_=(unsigned)__builtin_amdgcn_readfirstlane(NT>2?kdst+2*SLOT16:ddst); glds16s(g_,voff,d_); glds16s(g_+8192,voff,d_+8192); }
;   float mhat=0.f,l=0.f;
;   f32x16 o[4];
;   #pragma unroll
;   for(int d0=0;d0<4;++d0)o[d0]=f32x16{};
;   const int qpos=qw0+r32;
;   f32x16 p0,p1; u32x4 pw[4]; bf16x8 kf[8]; bf16x8 va[4],vb[4];
;   f32x16 cini;
;   #pragma unroll
;   for(int r=0;r<16;++r)cini[r]=cfar;
;   asm volatile("":"+v"(cini));
;     ...
;   WAIT_BAR(8);
;   KRD(kp0);
;   int ks_t=0,ks_n=SLOT16,vs_t=0,vs_nn=2*SLOT16;
;   for(int t=0;t<NT;++t){
;     WAIT_BAR(4);
;     const int kv0=t*KVBLK;
;     const bool act=(kv0<=qw0+QBLK-1);
;     const bool actn=(t+1<NT)&&(kv0+KVBLK<=qw0+QBLK-1);
;     const lds_cptr vp=vp0+vs_t;
;     const bool dk=(t+3<NT), dv=(t+2<NT);
;     const unsigned char*gk_=imgS+((size_t)(dk?t+3:NT-1)<<15); const unsigned char*gv_=imgS+((size_t)(dv?t+2:NT-1)<<15)+16384;
;     const unsigned kd_=(unsigned)__builtin_amdgcn_readfirstlane(dk?kdst+ks_t:ddst), vd_=(unsigned)__builtin_amdgcn_readfirstlane(dv?vdst+vs_nn:ddst);
;     if(act){
;       VRK(va,vp,0); VRK(vb,vp,1);
;       SBAR();
;       QKM(cini);
;     }
;     if(act){
;       const bool far=(qw0-(kv0+63)>=113);
;       if(!far){ const float*bt=biasT+mp*128; const int dq=qpos-kv0-4*hi;
;         #pragma unroll
;         for(int r=0;r<16;++r){ const int d=dq-((r&3)+8*(r>>2));
;           const int i0=d<0?0:(d>127?127:d);
;           const float b0=bt[i0];
;           const float n0=d>=0?0.f:-INFINITY;
;           p0[r]=(p0[r]+(b0-cfar))+n0; if((r&7)==7)asm volatile("":::"memory"); }
;         #pragma unroll
;         for(int r=0;r<16;++r){ const int d1=dq-32-((r&3)+8*(r>>2));
;           const int i1=d1<0?0:(d1>127?127:d1);
;           const float b1=bt[i1];
;           const float n1=d1>=0?0.f:-INFINITY;
;           p1[r]=(p1[r]+(b1-cfar))+n1; if((r&7)==7)asm volatile("":::"memory"); } }
.LBB0_242:
	s_min_u32 s20, s81, 3
	s_or_b32 s80, s40, 31
	s_lshl_b32 s20, s20, 15
	s_add_u32 s94, s42, s20
	s_addc_u32 s95, s43, 0
	s_add_u32 s20, s8, 0x4000
	s_addc_u32 s21, s9, 0
	s_mov_b32 s40, m0
	s_mov_b32 m0, s82
	s_nop 0
	global_load_lds_dwordx4 v209, s[94:95]
	s_mov_b32 m0, s40
	s_add_u32 s94, s94, 0x2000
	s_addc_u32 s95, s95, 0
	s_addk_i32 s82, 0x2000
	s_mov_b32 s40, m0
	s_mov_b32 m0, s82
	s_nop 0
	global_load_lds_dwordx4 v209, s[94:95]
	s_mov_b32 m0, s40
	s_add_u32 s8, s8, 0x6000
	s_mov_b32 s40, m0
	s_mov_b32 m0, s73
	s_nop 0
	global_load_lds_dwordx4 v209, s[20:21]
	s_mov_b32 m0, s40
	s_addc_u32 s9, s9, 0
	s_addk_i32 s73, 0x2000
	s_mov_b32 s20, m0
	s_mov_b32 m0, s73
	s_nop 0
	global_load_lds_dwordx4 v209, s[8:9]
	s_mov_b32 m0, s20
	s_add_i32 s20, s22, s23
	s_mov_b32 s41, 3
	s_mov_b32 s9, 0
	s_add_i32 s8, s72, 2
	s_add_i32 s22, s20, 0xffffff81
	s_waitcnt vmcnt(8)
	v_add_u32_e32 v14, 0x2000, v209
	s_mov_b32 s23, 0x8000
	s_movk_i32 s73, 0x4000
	s_mov_b32 s40, 64
	s_movk_i32 s94, 0x4000
.LBB0_243:
	s_add_i32 s95, s41, 1
	s_add_i32 s20, s94, s46
	s_cmp_lt_i32 s41, s81
	s_cselect_b32 s82, s20, s98
	s_add_i32 s20, s9, s99
	s_waitcnt vmcnt(4) lgkmcnt(0)
	s_barrier
	s_cmp_lt_i32 s41, s72
	s_cselect_b32 s73, s20, s98
	s_cmp_lt_i32 s22, 0xffffffa2
	s_cbranch_scc1 .Ltr_inact
	v_add_u32_e32 v15, s94, v210
	ds_read_b128 v[162:165], v15 offset:49152
	ds_read_b128 v[146:149], v15 offset:50176
	ds_read_b128 v[158:161], v15 offset:53248
	ds_read_b128 v[10:13], v15 offset:54272
	ds_read_b128 v[154:157], v15 offset:57344
	ds_read_b128 v[6:9], v15 offset:58368
	ds_read_b128 v[150:153], v15 offset:61440
	ds_read_b128 v[2:5], v15 offset:62464
	v_mfma_f32_32x32x16_bf16 v[114:129], v[178:181], v[130:133], v[82:97]
	s_cmpk_gt_i32 s22, 0x70
	v_mfma_f32_32x32x16_bf16 v[98:113], v[182:185], v[130:133], v[82:97]
	v_mfma_f32_32x32x16_bf16 v[98:113], v[186:189], v[134:137], v[98:113]
	v_mfma_f32_32x32x16_bf16 v[114:129], v[166:169], v[134:137], v[114:129]
	v_mfma_f32_32x32x16_bf16 v[98:113], v[190:193], v[138:141], v[98:113]
	v_mfma_f32_32x32x16_bf16 v[114:129], v[174:177], v[138:141], v[114:129]
	v_mfma_f32_32x32x16_bf16 v[98:113], v[194:197], v[142:145], v[98:113]
	v_mfma_f32_32x32x16_bf16 v[114:129], v[170:173], v[142:145], v[114:129]
	s_cbranch_scc1 .LBB0_246
	v_lshlrev_b32_e32 v212, 2, v206
	v_sub_u32_e32 v212, v208, v212
	v_add_u32_e32 v212, s22, v212
	s_sub_i32 s20, s29, 0x18800
	s_lshl_b32 s20, s20, 1
	s_add_i32 s20, s20, 0x1d000
	v_lshl_add_u32 v213, v212, 2, s20
	ds_read_b32 v166, v213 offset:504
	ds_read_b32 v167, v213 offset:500
	ds_read_b32 v168, v213 offset:496
	ds_read_b32 v169, v213 offset:492
	ds_read_b32 v170, v213 offset:472
	ds_read_b32 v171, v213 offset:468
	ds_read_b32 v172, v213 offset:464
	ds_read_b32 v173, v213 offset:460
	ds_read_b32 v174, v213 offset:440
	ds_read_b32 v175, v213 offset:436
	ds_read_b32 v176, v213 offset:432
	ds_read_b32 v177, v213 offset:428
	ds_read_b32 v178, v213 offset:408
	ds_read_b32 v179, v213 offset:404
	ds_read_b32 v180, v213 offset:400
	ds_read_b32 v181, v213 offset:396
	ds_read_b32 v182, v213 offset:376
	ds_read_b32 v183, v213 offset:372
	ds_read_b32 v184, v213 offset:368
	ds_read_b32 v185, v213 offset:364
	ds_read_b32 v186, v213 offset:344
	ds_read_b32 v187, v213 offset:340
	ds_read_b32 v188, v213 offset:336
	ds_read_b32 v189, v213 offset:332
	ds_read_b32 v190, v213 offset:312
	ds_read_b32 v191, v213 offset:308
	ds_read_b32 v192, v213 offset:304
	ds_read_b32 v193, v213 offset:300
	ds_read_b32 v194, v213 offset:280
	ds_read_b32 v195, v213 offset:276
	ds_read_b32 v196, v213 offset:272
	ds_read_b32 v197, v213 offset:268
	s_waitcnt lgkmcnt(14)
	v_pk_add_f32 v[114:115], v[114:115], v[166:167]
	v_pk_add_f32 v[116:117], v[116:117], v[168:169]
	v_pk_add_f32 v[118:119], v[118:119], v[170:171]
	v_pk_add_f32 v[120:121], v[120:121], v[172:173]
	v_pk_add_f32 v[122:123], v[122:123], v[174:175]
	v_pk_add_f32 v[124:125], v[124:125], v[176:177]
	v_pk_add_f32 v[126:127], v[126:127], v[178:179]
	v_pk_add_f32 v[128:129], v[128:129], v[180:181]
	s_waitcnt lgkmcnt(0)
	v_pk_add_f32 v[98:99], v[98:99], v[182:183]
	v_pk_add_f32 v[100:101], v[100:101], v[184:185]
	v_pk_add_f32 v[102:103], v[102:103], v[186:187]
	v_pk_add_f32 v[104:105], v[104:105], v[188:189]
	v_pk_add_f32 v[106:107], v[106:107], v[190:191]
	v_pk_add_f32 v[108:109], v[108:109], v[192:193]
	v_pk_add_f32 v[110:111], v[110:111], v[194:195]
	v_pk_add_f32 v[112:113], v[112:113], v[196:197]

; template<int THRL> __device__ __forceinline__ void attn_unit(int b,int h,int qb,const AttnArgs&A,char*shm,bool setup){
;     ...
;     glds16s(gk_,voff,kd_); glds16s(gk_+8192,voff,kd_+8192); glds16s(gv_,voff,vd_); glds16s(gv_+8192,voff,vd_+8192);
;     ks_t=ks_n; ks_n=(ks_n==2*SLOT16)?0:ks_n+SLOT16; vs_t=(vs_t==2*SLOT16)?0:vs_t+SLOT16; vs_nn=(vs_nn==2*SLOT16)?0:vs_nn+SLOT16;
.LBB0_249:
	s_mov_b32 m0, s82
	s_add_i32 s41, s41, 1
	global_load_lds_dwordx4 v209, s[20:21]
	s_mov_b32 m0, s83
	s_sub_i32 s22, s22, 64
	global_load_lds_dwordx4 v14, s[20:21]
	s_mov_b32 m0, s73
	s_mov_b32 s83, s94
	global_load_lds_dwordx4 v209, s[84:85]
	s_mov_b32 m0, s95
	s_mov_b32 s94, s23
	global_load_lds_dwordx4 v14, s[84:85]
	s_mov_b32 s23, s9
	s_mov_b32 s9, s83
	s_cmp_lg_u32 s41, s8
	s_cbranch_scc1 .LBB0_243
	s_branch .LBB0_252
